# prep phases: non-temporal (nt) loads for the read-once f32 inputs (x, weights)
# speedup vs baseline: 1.0167x; 1.0127x over previous
.LBB0_17:
	s_load_dwordx16 s[4:19], s[0:1], 0x0
	s_add_u32 s3, s42, 0x9800000
	s_addc_u32 s28, s43, 0
	s_cmpk_lt_i32 s85, 0x200
	s_cselect_b64 s[0:1], -1, 0
	s_waitcnt lgkmcnt(0)
	v_writelane_b32 v252, s4, 4
	v_mov_b32_e32 v10, v170
	s_cmpk_gt_i32 s85, 0x1ff
	v_writelane_b32 v252, s5, 5
	v_writelane_b32 v252, s6, 6
	v_writelane_b32 v252, s7, 7
	v_writelane_b32 v252, s8, 8
	v_writelane_b32 v252, s9, 9
	v_writelane_b32 v252, s10, 10
	v_writelane_b32 v252, s11, 11
	v_writelane_b32 v252, s12, 12
	v_writelane_b32 v252, s13, 13
	v_writelane_b32 v252, s14, 14
	v_writelane_b32 v252, s15, 15
	v_writelane_b32 v252, s16, 16
	v_writelane_b32 v252, s17, 17
	v_writelane_b32 v252, s18, 18
	v_writelane_b32 v252, s19, 19
	v_writelane_b32 v252, s0, 20
	s_nop 1
	v_writelane_b32 v252, s1, 21
	s_cbranch_scc1 .LBB0_22
	s_ashr_i32 s0, s85, 31
	s_lshr_b32 s0, s0, 26
	s_add_i32 s1, s85, s0
	s_ashr_i32 s0, s1, 6
	s_and_b32 s1, s1, 0xffc0
	s_sub_i32 s1, s85, s1
	s_bfe_i32 s2, s1, 0x80000
	s_bfe_u32 s2, s2, 0x3000c
	s_add_i32 s2, s1, s2
	s_bfe_i32 s4, s2, 0x80000
	s_and_b32 s2, s2, 0xf8
	s_sub_i32 s1, s1, s2
	s_sext_i32_i8 s2, s1
	s_ashr_i32 s1, s0, 31
	v_readlane_b32 s8, v252, 4
	s_lshl_b64 s[0:1], s[0:1], 20
	v_readlane_b32 s12, v252, 8
	s_sext_i32_i16 s4, s4
	v_readlane_b32 s13, v252, 9
	s_add_u32 s5, s12, s0
	s_addc_u32 s6, s13, s1
	s_lshl_b32 s0, s4, 3
	s_and_b32 s4, s0, 0xffffffc0
	s_lshl_b32 s0, s2, 6
	s_ashr_i32 s1, s0, 31
	s_lshl_b64 s[0:1], s[0:1], 2
	v_lshlrev_b32_e32 v0, 2, v10
	v_ashrrev_i32_e32 v12, 4, v10
	s_add_u32 s0, s5, s0
	v_and_b32_e32 v18, 60, v0
	v_add_u32_e32 v2, s4, v12
	s_addc_u32 s1, s6, s1
	v_mov_b32_e32 v9, 0
	v_lshlrev_b32_e32 v8, 2, v18
	v_ashrrev_i32_e32 v3, 31, v2
	v_lshl_add_u64 v[0:1], s[0:1], 0, v[8:9]
	v_lshlrev_b64 v[2:3], 11, v[2:3]
	v_lshl_add_u64 v[14:15], v[0:1], 0, v[2:3]
	v_add_u32_e32 v2, 0x200, v10
	v_ashrrev_i32_e32 v13, 4, v2
	v_add_u32_e32 v2, s4, v13
	v_ashrrev_i32_e32 v3, 31, v2
	v_lshlrev_b64 v[2:3], 11, v[2:3]
	v_lshl_add_u64 v[16:17], v[0:1], 0, v[2:3]
	global_load_dwordx4 v[0:3], v[14:15], off nt
	global_load_dwordx4 v[4:7], v[16:17], off nt
	v_add_u32_e32 v11, 0, v8
	v_lshlrev_b32_e32 v8, 3, v10
	v_ashrrev_i32_e32 v14, 3, v10
	v_and_b32_e32 v8, 56, v8
	s_movk_i32 s0, 0x104
	v_mul_u32_u24_e32 v10, 0x104, v8
	v_lshlrev_b32_e32 v15, 2, v14
	v_add3_u32 v15, 0, v10, v15
	v_mul_lo_u32 v10, v12, s0
	v_mul_lo_u32 v17, v13, s0
	v_add_u32_e32 v16, v11, v10
	v_add_u32_e32 v17, v11, v17
	v_lshlrev_b32_e32 v10, 2, v18
	v_lshlrev_b32_e32 v8, 1, v8
	s_mov_b32 s4, s85
	v_readlane_b32 s9, v252, 5
	v_readlane_b32 s10, v252, 6
	v_readlane_b32 s11, v252, 7
	v_readlane_b32 s14, v252, 10
	v_readlane_b32 s15, v252, 11
	v_readlane_b32 s16, v252, 12
	v_readlane_b32 s17, v252, 13
	v_readlane_b32 s18, v252, 14
	v_readlane_b32 s19, v252, 15
	v_readlane_b32 s20, v252, 16
	v_readlane_b32 s21, v252, 17
	v_readlane_b32 s22, v252, 18
	v_readlane_b32 s23, v252, 19
	s_branch .LBB0_20

.LBB0_20:
	s_add_i32 s2, s4, s92
	s_cmpk_gt_i32 s2, 0x1ff
	s_cselect_b64 s[0:1], -1, 0
	s_and_b64 vcc, exec, s[0:1]
	s_waitcnt vmcnt(1)
	ds_write2_b32 v16, v0, v1 offset1:1
	ds_write2_b32 v16, v2, v3 offset0:2 offset1:3
	s_waitcnt vmcnt(0)
	ds_write2_b32 v17, v4, v5 offset1:1
	ds_write2_b32 v17, v6, v7 offset0:2 offset1:3
	s_cbranch_vccnz .LBB0_19
	s_ashr_i32 s5, s2, 31
	s_lshr_b32 s5, s5, 26
	s_add_i32 s5, s2, s5
	s_ashr_i32 s6, s5, 6
	s_and_b32 s5, s5, 0xffc0
	s_sub_i32 s5, s2, s5
	s_bfe_i32 s7, s5, 0x80000
	s_bfe_u32 s7, s7, 0x3000c
	s_add_i32 s7, s5, s7
	s_bfe_i32 s8, s7, 0x80000
	s_and_b32 s7, s7, 0xf8
	s_sub_i32 s5, s5, s7
	s_ashr_i32 s7, s6, 31
	v_readlane_b32 s12, v252, 4
	s_lshl_b64 s[6:7], s[6:7], 20
	v_readlane_b32 s16, v252, 8
	s_sext_i32_i16 s8, s8
	v_readlane_b32 s17, v252, 9
	s_add_u32 s9, s16, s6
	s_sext_i32_i8 s5, s5
	s_addc_u32 s10, s17, s7
	s_lshl_b32 s6, s8, 3
	s_and_b32 s8, s6, 0xffffffc0
	s_lshl_b32 s6, s5, 6
	s_ashr_i32 s7, s6, 31
	s_lshl_b64 s[6:7], s[6:7], 2
	s_add_u32 s6, s9, s6
	v_add_u32_e32 v2, s8, v12
	s_addc_u32 s7, s10, s7
	v_mov_b32_e32 v11, v9
	v_ashrrev_i32_e32 v3, 31, v2
	v_lshl_add_u64 v[0:1], s[6:7], 0, v[10:11]
	v_lshlrev_b64 v[2:3], 11, v[2:3]
	v_lshl_add_u64 v[18:19], v[0:1], 0, v[2:3]
	v_add_u32_e32 v2, s8, v13
	v_ashrrev_i32_e32 v3, 31, v2
	v_lshlrev_b64 v[2:3], 11, v[2:3]
	v_lshl_add_u64 v[20:21], v[0:1], 0, v[2:3]
	global_load_dwordx4 v[0:3], v[18:19], off nt
	global_load_dwordx4 v[4:7], v[20:21], off nt
	v_readlane_b32 s13, v252, 5
	v_readlane_b32 s14, v252, 6
	v_readlane_b32 s15, v252, 7
	v_readlane_b32 s18, v252, 10
	v_readlane_b32 s19, v252, 11
	v_readlane_b32 s20, v252, 12
	v_readlane_b32 s21, v252, 13
	v_readlane_b32 s22, v252, 14
	v_readlane_b32 s23, v252, 15
	v_readlane_b32 s24, v252, 16
	v_readlane_b32 s25, v252, 17
	v_readlane_b32 s26, v252, 18
	v_readlane_b32 s27, v252, 19
	s_branch .LBB0_19

.LBB0_25:
	v_ashrrev_i32_e32 v24, 18, v34
	v_ashrrev_i32_e32 v25, 31, v24
	v_readlane_b32 s44, v252, 4
	v_and_b32_e32 v27, 0x3ff000, v42
	v_lshlrev_b64 v[24:25], 24, v[24:25]
	v_readlane_b32 s46, v252, 6
	v_readlane_b32 s47, v252, 7
	v_lshlrev_b32_e32 v32, 2, v27
	v_lshrrev_b32_e32 v27, 5, v34
	v_lshl_add_u64 v[24:25], s[46:47], 0, v[24:25]
	v_and_b32_e32 v26, 0x1f8, v43
	v_lshl_add_u64 v[24:25], v[24:25], 0, v[32:33]
	v_and_b32_e32 v32, 0x1800, v27
	v_lshl_add_u64 v[24:25], v[24:25], 0, v[32:33]
	v_lshlrev_b32_e32 v32, 2, v26
	v_lshl_add_u64 v[28:29], v[24:25], 0, v[32:33]
	global_load_dwordx4 v[24:27], v[28:29], off offset:16 nt
	s_nop 0
	global_load_dwordx4 v[28:31], v[28:29], off nt
	v_add_u32_e32 v36, s15, v34
	v_cmp_gt_i32_e32 vcc, s14, v36
	v_readlane_b32 s45, v252, 5
	v_readlane_b32 s48, v252, 8
	v_readlane_b32 s49, v252, 9
	v_readlane_b32 s50, v252, 10
	v_readlane_b32 s51, v252, 11
	v_readlane_b32 s52, v252, 12
	v_readlane_b32 s53, v252, 13
	v_readlane_b32 s54, v252, 14
	v_readlane_b32 s55, v252, 15
	v_readlane_b32 s56, v252, 16
	v_readlane_b32 s57, v252, 17
	v_readlane_b32 s58, v252, 18
	v_readlane_b32 s59, v252, 19
	s_and_saveexec_b64 s[0:1], vcc
	s_cbranch_execz .LBB0_27
	v_ashrrev_i32_e32 v0, 18, v36
	v_ashrrev_i32_e32 v1, 31, v0
	v_add_u32_e32 v2, s21, v42
	v_readlane_b32 s44, v252, 4
	v_and_b32_e32 v2, 0x3ff000, v2
	v_lshlrev_b64 v[0:1], 24, v[0:1]
	v_readlane_b32 s46, v252, 6
	v_readlane_b32 s47, v252, 7
	v_lshlrev_b32_e32 v2, 2, v2
	v_mov_b32_e32 v3, v33
	v_lshl_add_u64 v[0:1], s[46:47], 0, v[0:1]
	v_lshl_add_u64 v[0:1], v[0:1], 0, v[2:3]
	v_lshrrev_b32_e32 v2, 5, v36
	v_and_b32_e32 v2, 0x1800, v2
	v_lshl_add_u64 v[0:1], v[0:1], 0, v[2:3]
	v_lshl_add_u64 v[0:1], v[0:1], 0, v[32:33]
	global_load_dwordx4 v[8:11], v[0:1], off offset:16 nt
	s_nop 0
	global_load_dwordx4 v[0:3], v[0:1], off nt
	v_readlane_b32 s45, v252, 5
	v_readlane_b32 s48, v252, 8
	v_readlane_b32 s49, v252, 9
	v_readlane_b32 s50, v252, 10
	v_readlane_b32 s51, v252, 11
	v_readlane_b32 s52, v252, 12
	v_readlane_b32 s53, v252, 13
	v_readlane_b32 s54, v252, 14
	v_readlane_b32 s55, v252, 15
	v_readlane_b32 s56, v252, 16
	v_readlane_b32 s57, v252, 17
	v_readlane_b32 s58, v252, 18
	v_readlane_b32 s59, v252, 19
.LBB0_27:
	s_or_b64 exec, exec, s[0:1]
	v_add_u32_e32 v38, s16, v34
	v_cmp_gt_i32_e64 s[4:5], s14, v38
	s_and_saveexec_b64 s[0:1], s[4:5]
	s_cbranch_execz .LBB0_29
	v_ashrrev_i32_e32 v4, 18, v38
	v_ashrrev_i32_e32 v5, 31, v4
	v_add_u32_e32 v6, s17, v42
	v_readlane_b32 s44, v252, 4
	v_and_b32_e32 v6, 0x3ff000, v6
	v_lshlrev_b64 v[4:5], 24, v[4:5]
	v_readlane_b32 s46, v252, 6
	v_readlane_b32 s47, v252, 7
	v_lshlrev_b32_e32 v6, 2, v6
	v_mov_b32_e32 v7, v33
	v_lshl_add_u64 v[4:5], s[46:47], 0, v[4:5]
	v_lshl_add_u64 v[4:5], v[4:5], 0, v[6:7]
	v_lshrrev_b32_e32 v6, 5, v38
	v_and_b32_e32 v6, 0x1800, v6
	v_lshl_add_u64 v[4:5], v[4:5], 0, v[6:7]
	v_lshl_add_u64 v[4:5], v[4:5], 0, v[32:33]
	global_load_dwordx4 v[16:19], v[4:5], off offset:16 nt
	s_nop 0
	global_load_dwordx4 v[4:7], v[4:5], off nt
	v_readlane_b32 s45, v252, 5
	v_readlane_b32 s48, v252, 8
	v_readlane_b32 s49, v252, 9
	v_readlane_b32 s50, v252, 10
	v_readlane_b32 s51, v252, 11
	v_readlane_b32 s52, v252, 12
	v_readlane_b32 s53, v252, 13
	v_readlane_b32 s54, v252, 14
	v_readlane_b32 s55, v252, 15
	v_readlane_b32 s56, v252, 16
	v_readlane_b32 s57, v252, 17
	v_readlane_b32 s58, v252, 18
	v_readlane_b32 s59, v252, 19
.LBB0_29:
	s_or_b64 exec, exec, s[0:1]
	v_add_u32_e32 v40, s19, v34
	v_cmp_gt_i32_e64 s[0:1], s14, v40
	s_and_saveexec_b64 s[12:13], s[0:1]
	s_cbranch_execz .LBB0_31
	v_ashrrev_i32_e32 v12, 18, v40
	v_ashrrev_i32_e32 v13, 31, v12
	v_add_u32_e32 v14, s20, v42
	v_readlane_b32 s44, v252, 4
	v_and_b32_e32 v14, 0x3ff000, v14
	v_lshlrev_b64 v[12:13], 24, v[12:13]
	v_readlane_b32 s46, v252, 6
	v_readlane_b32 s47, v252, 7
	v_lshlrev_b32_e32 v14, 2, v14
	v_mov_b32_e32 v15, v33
	v_lshl_add_u64 v[12:13], s[46:47], 0, v[12:13]
	v_lshl_add_u64 v[12:13], v[12:13], 0, v[14:15]
	v_lshrrev_b32_e32 v14, 5, v40
	v_and_b32_e32 v14, 0x1800, v14
	v_lshl_add_u64 v[12:13], v[12:13], 0, v[14:15]
	v_lshl_add_u64 v[12:13], v[12:13], 0, v[32:33]
	global_load_dwordx4 v[20:23], v[12:13], off offset:16 nt
	s_nop 0
	global_load_dwordx4 v[12:15], v[12:13], off nt
	v_readlane_b32 s45, v252, 5
	v_readlane_b32 s48, v252, 8
	v_readlane_b32 s49, v252, 9
	v_readlane_b32 s50, v252, 10
	v_readlane_b32 s51, v252, 11
	v_readlane_b32 s52, v252, 12
	v_readlane_b32 s53, v252, 13
	v_readlane_b32 s54, v252, 14
	v_readlane_b32 s55, v252, 15
	v_readlane_b32 s56, v252, 16
	v_readlane_b32 s57, v252, 17
	v_readlane_b32 s58, v252, 18
	v_readlane_b32 s59, v252, 19

.LBB0_97:
	s_cmpk_lt_i32 s85, 0x400
	v_mov_b32_e32 v10, v170
	s_cselect_b64 s[0:1], -1, 0
	s_cmpk_gt_i32 s85, 0x3ff
	s_cbranch_scc1 .LBB0_102
	s_add_u32 s3, s42, 0x8400000
	s_addc_u32 s6, s43, 0
	s_ashr_i32 s4, s85, 31
	s_lshr_b32 s4, s4, 23
	s_add_i32 s5, s85, s4
	s_ashr_i32 s4, s5, 9
	s_and_b32 s5, s5, 0xfe00
	s_sub_i32 s5, s85, s5
	s_sext_i32_i16 s7, s5
	s_bfe_u32 s7, s7, 0x5001a
	s_add_i32 s7, s5, s7
	s_sext_i32_i16 s8, s7
	s_and_b32 s7, s7, 0xffe0
	s_sub_i32 s5, s5, s7
	s_sext_i32_i16 s7, s5
	s_ashr_i32 s5, s4, 31
	v_readlane_b32 s12, v252, 4
	s_lshl_b64 s[4:5], s[4:5], 24
	v_readlane_b32 s14, v252, 6
	v_readlane_b32 s15, v252, 7
	s_add_u32 s9, s14, s4
	s_addc_u32 s12, s15, s5
	s_lshl_b32 s4, s8, 1
	s_and_b32 s8, s4, 0xffffffc0
	s_lshl_b32 s4, s7, 6
	s_ashr_i32 s5, s4, 31
	s_lshl_b64 s[4:5], s[4:5], 2
	v_lshlrev_b32_e32 v0, 2, v10
	s_add_u32 s4, s9, s4
	v_and_b32_e32 v18, 60, v0
	v_ashrrev_i32_e32 v12, 4, v10
	s_addc_u32 s5, s12, s5
	v_mov_b32_e32 v9, 0
	v_lshlrev_b32_e32 v8, 2, v18
	v_add_u32_e32 v2, s8, v12
	v_lshl_add_u64 v[0:1], s[4:5], 0, v[8:9]
	s_mov_b64 s[4:5], 0x2000
	v_ashrrev_i32_e32 v3, 31, v2
	v_lshl_add_u64 v[0:1], v[0:1], 0, s[4:5]
	v_lshlrev_b64 v[2:3], 14, v[2:3]
	v_lshl_add_u64 v[14:15], v[0:1], 0, v[2:3]
	v_add_u32_e32 v2, 0x200, v10
	v_ashrrev_i32_e32 v13, 4, v2
	v_add_u32_e32 v2, s8, v13
	v_ashrrev_i32_e32 v3, 31, v2
	v_lshlrev_b64 v[2:3], 14, v[2:3]
	v_lshl_add_u64 v[16:17], v[0:1], 0, v[2:3]
	global_load_dwordx4 v[0:3], v[14:15], off nt
	global_load_dwordx4 v[4:7], v[16:17], off nt
	v_add_u32_e32 v11, 0, v8
	v_lshlrev_b32_e32 v8, 3, v10
	v_ashrrev_i32_e32 v14, 3, v10
	v_and_b32_e32 v8, 56, v8
	s_movk_i32 s4, 0x104
	v_mul_u32_u24_e32 v10, 0x104, v8
	v_lshlrev_b32_e32 v15, 2, v14
	s_add_u32 s7, s14, 0x2000
	v_add3_u32 v15, 0, v10, v15
	v_mul_lo_u32 v10, v12, s4
	v_mul_lo_u32 v17, v13, s4
	s_addc_u32 s8, s15, 0
	v_add_u32_e32 v16, v11, v10
	v_add_u32_e32 v17, v11, v17
	v_lshlrev_b32_e32 v10, 2, v18
	v_lshlrev_b32_e32 v8, 1, v8
	s_mov_b32 s12, s85
	v_readlane_b32 s13, v252, 5
	v_readlane_b32 s16, v252, 8
	v_readlane_b32 s17, v252, 9
	v_readlane_b32 s18, v252, 10
	v_readlane_b32 s19, v252, 11
	v_readlane_b32 s20, v252, 12
	v_readlane_b32 s21, v252, 13
	v_readlane_b32 s22, v252, 14
	v_readlane_b32 s23, v252, 15
	v_readlane_b32 s24, v252, 16
	v_readlane_b32 s25, v252, 17
	v_readlane_b32 s26, v252, 18
	v_readlane_b32 s27, v252, 19
	s_branch .LBB0_100

.LBB0_100:
	s_add_i32 s9, s12, s92
	s_cmpk_gt_i32 s9, 0x3ff
	s_cselect_b64 s[4:5], -1, 0
	s_and_b64 vcc, exec, s[4:5]
	s_waitcnt vmcnt(0)
	ds_write2_b32 v16, v0, v1 offset1:1
	ds_write2_b32 v16, v2, v3 offset0:2 offset1:3
	ds_write2_b32 v17, v4, v5 offset1:1
	ds_write2_b32 v17, v6, v7 offset0:2 offset1:3
	s_cbranch_vccnz .LBB0_99
	s_ashr_i32 s13, s9, 31
	s_lshr_b32 s13, s13, 23
	s_add_i32 s13, s9, s13
	s_ashr_i32 s14, s13, 9
	s_and_b32 s13, s13, 0xfe00
	s_sub_i32 s13, s9, s13
	s_sext_i32_i16 s15, s13
	s_bfe_u32 s15, s15, 0x5001a
	s_add_i32 s15, s13, s15
	s_sext_i32_i16 s16, s15
	s_and_b32 s15, s15, 0xffe0
	s_sub_i32 s13, s13, s15
	s_ashr_i32 s15, s14, 31
	s_lshl_b64 s[14:15], s[14:15], 24
	s_add_u32 s17, s7, s14
	s_sext_i32_i16 s13, s13
	s_addc_u32 s18, s8, s15
	s_lshl_b32 s14, s16, 1
	s_and_b32 s16, s14, 0xffffffc0
	s_lshl_b32 s14, s13, 6
	s_ashr_i32 s15, s14, 31
	s_lshl_b64 s[14:15], s[14:15], 2
	s_add_u32 s14, s17, s14
	v_add_u32_e32 v2, s16, v12
	s_addc_u32 s15, s18, s15
	v_mov_b32_e32 v11, v9
	v_ashrrev_i32_e32 v3, 31, v2
	v_lshl_add_u64 v[0:1], s[14:15], 0, v[10:11]
	v_lshlrev_b64 v[2:3], 14, v[2:3]
	v_lshl_add_u64 v[18:19], v[0:1], 0, v[2:3]
	v_add_u32_e32 v2, s16, v13
	v_ashrrev_i32_e32 v3, 31, v2
	v_lshlrev_b64 v[2:3], 14, v[2:3]
	v_lshl_add_u64 v[20:21], v[0:1], 0, v[2:3]
	global_load_dwordx4 v[0:3], v[18:19], off nt
	global_load_dwordx4 v[4:7], v[20:21], off nt
	s_branch .LBB0_99
.LBB0_102:
	s_add_u32 s64, s42, 0x9000000
	s_waitcnt vmcnt(0)
	v_cndmask_b32_e64 v0, 0, 1, s[0:1]
	s_addc_u32 s65, s43, 0
	v_mov_b32_e32 v10, v170
	v_cmp_ne_u32_e64 s[8:9], 1, v0
	s_andn2_b64 vcc, exec, s[0:1]
	s_cbranch_vccnz .LBB0_107
	s_ashr_i32 s0, s85, 31
	s_lshr_b32 s0, s0, 23
	s_add_i32 s1, s85, s0
	s_ashr_i32 s0, s1, 9
	s_and_b32 s1, s1, 0xfe00
	s_sub_i32 s1, s85, s1
	s_sext_i32_i16 s3, s1
	s_bfe_u32 s3, s3, 0x4001b
	s_add_i32 s3, s1, s3
	s_sext_i32_i16 s4, s3
	s_and_b32 s3, s3, 0xfff0
	s_sub_i32 s1, s1, s3
	s_sext_i32_i16 s3, s1
	s_ashr_i32 s1, s0, 31
	v_readlane_b32 s12, v252, 4
	s_lshl_b64 s[0:1], s[0:1], 23
	v_readlane_b32 s20, v252, 12
	v_readlane_b32 s21, v252, 13
	s_add_u32 s5, s20, s0
	s_addc_u32 s6, s21, s1
	s_lshl_b32 s0, s4, 2
	s_and_b32 s4, s0, 0xffffffc0
	s_lshl_b32 s0, s3, 6
	s_ashr_i32 s1, s0, 31
	s_lshl_b64 s[0:1], s[0:1], 2
	v_lshlrev_b32_e32 v0, 2, v10
	v_ashrrev_i32_e32 v12, 4, v10
	s_add_u32 s0, s5, s0
	v_and_b32_e32 v18, 60, v0
	v_add_u32_e32 v2, s4, v12
	s_addc_u32 s1, s6, s1
	v_mov_b32_e32 v9, 0
	v_lshlrev_b32_e32 v8, 2, v18
	v_ashrrev_i32_e32 v3, 31, v2
	v_lshl_add_u64 v[0:1], s[0:1], 0, v[8:9]
	v_lshlrev_b64 v[2:3], 12, v[2:3]
	v_lshl_add_u64 v[14:15], v[0:1], 0, v[2:3]
	v_add_u32_e32 v2, 0x200, v10
	v_ashrrev_i32_e32 v13, 4, v2
	v_add_u32_e32 v2, s4, v13
	v_ashrrev_i32_e32 v3, 31, v2
	v_lshlrev_b64 v[2:3], 12, v[2:3]
	v_lshl_add_u64 v[16:17], v[0:1], 0, v[2:3]
	global_load_dwordx4 v[0:3], v[14:15], off nt
	global_load_dwordx4 v[4:7], v[16:17], off nt
	v_add_u32_e32 v11, 0, v8
	v_lshlrev_b32_e32 v8, 3, v10
	v_ashrrev_i32_e32 v14, 3, v10
	v_and_b32_e32 v8, 56, v8
	s_movk_i32 s0, 0x104
	v_mul_u32_u24_e32 v10, 0x104, v8
	v_lshlrev_b32_e32 v15, 2, v14
	v_add3_u32 v15, 0, v10, v15
	v_mul_lo_u32 v10, v12, s0
	v_mul_lo_u32 v17, v13, s0
	v_add_u32_e32 v16, v11, v10
	v_add_u32_e32 v17, v11, v17
	v_lshlrev_b32_e32 v10, 2, v18
	v_lshlrev_b32_e32 v8, 1, v8
	s_mov_b32 s4, s85
	v_readlane_b32 s13, v252, 5
	v_readlane_b32 s14, v252, 6
	v_readlane_b32 s15, v252, 7
	v_readlane_b32 s16, v252, 8
	v_readlane_b32 s17, v252, 9
	v_readlane_b32 s18, v252, 10
	v_readlane_b32 s19, v252, 11
	v_readlane_b32 s22, v252, 14
	v_readlane_b32 s23, v252, 15
	v_readlane_b32 s24, v252, 16
	v_readlane_b32 s25, v252, 17
	v_readlane_b32 s26, v252, 18
	v_readlane_b32 s27, v252, 19
	s_branch .LBB0_105

.LBB0_105:
	s_add_i32 s3, s4, s92
	s_cmpk_gt_i32 s3, 0x3ff
	s_cselect_b64 s[0:1], -1, 0
	s_and_b64 vcc, exec, s[0:1]
	s_waitcnt vmcnt(1)
	ds_write2_b32 v16, v0, v1 offset1:1
	ds_write2_b32 v16, v2, v3 offset0:2 offset1:3
	s_waitcnt vmcnt(0)
	ds_write2_b32 v17, v4, v5 offset1:1
	ds_write2_b32 v17, v6, v7 offset0:2 offset1:3
	s_cbranch_vccnz .LBB0_104
	s_ashr_i32 s5, s3, 31
	s_lshr_b32 s5, s5, 23
	s_add_i32 s5, s3, s5
	s_ashr_i32 s6, s5, 9
	s_and_b32 s5, s5, 0xfe00
	s_sub_i32 s5, s3, s5
	s_sext_i32_i16 s7, s5
	s_bfe_u32 s7, s7, 0x4001b
	s_add_i32 s7, s5, s7
	s_sext_i32_i16 s12, s7
	s_and_b32 s7, s7, 0xfff0
	s_sub_i32 s5, s5, s7
	s_ashr_i32 s7, s6, 31
	v_readlane_b32 s16, v252, 4
	s_lshl_b64 s[6:7], s[6:7], 23
	v_readlane_b32 s24, v252, 12
	v_readlane_b32 s25, v252, 13
	s_add_u32 s13, s24, s6
	s_sext_i32_i16 s5, s5
	s_addc_u32 s14, s25, s7
	s_lshl_b32 s6, s12, 2
	s_and_b32 s12, s6, 0xffffffc0
	s_lshl_b32 s6, s5, 6
	s_ashr_i32 s7, s6, 31
	s_lshl_b64 s[6:7], s[6:7], 2
	s_add_u32 s6, s13, s6
	v_add_u32_e32 v2, s12, v12
	s_addc_u32 s7, s14, s7
	v_mov_b32_e32 v11, v9
	v_ashrrev_i32_e32 v3, 31, v2
	v_lshl_add_u64 v[0:1], s[6:7], 0, v[10:11]
	v_lshlrev_b64 v[2:3], 12, v[2:3]
	v_lshl_add_u64 v[18:19], v[0:1], 0, v[2:3]
	v_add_u32_e32 v2, s12, v13
	v_ashrrev_i32_e32 v3, 31, v2
	v_lshlrev_b64 v[2:3], 12, v[2:3]
	v_lshl_add_u64 v[20:21], v[0:1], 0, v[2:3]
	global_load_dwordx4 v[0:3], v[18:19], off nt
	global_load_dwordx4 v[4:7], v[20:21], off nt
	v_readlane_b32 s17, v252, 5
	v_readlane_b32 s18, v252, 6
	v_readlane_b32 s19, v252, 7
	v_readlane_b32 s20, v252, 8
	v_readlane_b32 s21, v252, 9
	v_readlane_b32 s22, v252, 10
	v_readlane_b32 s23, v252, 11
	v_readlane_b32 s26, v252, 14
	v_readlane_b32 s27, v252, 15
	v_readlane_b32 s28, v252, 16
	v_readlane_b32 s29, v252, 17
	v_readlane_b32 s30, v252, 18
	v_readlane_b32 s31, v252, 19
	s_branch .LBB0_104
.LBB0_107:
	s_add_u32 s0, s42, 0xc000000
	s_addc_u32 s1, s43, 0
	v_writelane_b32 v252, s0, 22
	v_mov_b32_e32 v10, v170
	s_cmpk_gt_i32 s85, 0x5ff
	v_writelane_b32 v252, s1, 23
	s_cbranch_scc1 .LBB0_112
	s_mul_hi_i32 s0, s85, 0x2aaaaaab
	s_lshr_b32 s1, s0, 31
	s_lshr_b32 s0, s0, 8
	s_add_i32 s0, s0, s1
	s_mulk_i32 s0, 0x600
	s_sub_i32 s0, s85, s0
	s_mul_i32 s1, s0, 0x2aab
	s_lshr_b32 s3, s1, 31
	s_ashr_i32 s1, s1, 20
	s_add_i32 s1, s1, s3
	s_mul_i32 s3, s1, 0x60
	s_sub_i32 s0, s0, s3
	s_sext_i32_i16 s0, s0
	s_lshl_b32 s0, s0, 6
	s_lshl_b32 s4, s1, 6
	s_ashr_i32 s1, s0, 31
	v_readlane_b32 s12, v252, 4
	s_lshl_b64 s[0:1], s[0:1], 2
	v_readlane_b32 s22, v252, 14
	v_readlane_b32 s23, v252, 15
	s_add_u32 s0, s22, s0
	s_waitcnt vmcnt(2)
	v_lshlrev_b32_e32 v0, 4, v10
	s_addc_u32 s1, s23, s1
	v_and_b32_e32 v8, 0xf0, v0
	v_mov_b32_e32 v9, 0
	v_ashrrev_i32_e32 v12, 4, v10
	v_lshl_add_u64 v[0:1], s[0:1], 0, v[8:9]
	v_add_u32_e32 v2, s4, v12
	s_movk_i32 s3, 0x6000
	v_mad_i64_i32 v[14:15], s[0:1], v2, s3, v[0:1]
	v_add_u32_e32 v2, 0x200, v10
	v_ashrrev_i32_e32 v13, 4, v2
	v_add_u32_e32 v2, s4, v13
	v_mad_i64_i32 v[16:17], s[0:1], v2, s3, v[0:1]
	global_load_dwordx4 v[0:3], v[14:15], off nt
	global_load_dwordx4 v[4:7], v[16:17], off nt
	v_ashrrev_i32_e32 v14, 3, v10
	v_lshlrev_b32_e32 v10, 3, v10
	v_and_b32_e32 v18, 56, v10
	s_movk_i32 s0, 0x104
	v_mul_u32_u24_e32 v10, 0x104, v18
	v_lshlrev_b32_e32 v11, 2, v14
	v_add_u32_e32 v17, 0, v8
	v_add3_u32 v15, 0, v10, v11
	v_mul_lo_u32 v16, v12, s0
	v_mul_lo_u32 v19, v13, s0
	v_lshl_add_u64 v[10:11], s[22:23], 0, v[8:9]
	v_add_u32_e32 v16, v17, v16
	v_add_u32_e32 v17, v17, v19
	v_lshlrev_b32_e32 v8, 1, v18
	v_add_u32_e32 v18, 0x400, v15
	s_mov_b32 s5, s85
	v_readlane_b32 s13, v252, 5
	v_readlane_b32 s14, v252, 6
	v_readlane_b32 s15, v252, 7
	v_readlane_b32 s16, v252, 8
	v_readlane_b32 s17, v252, 9
	v_readlane_b32 s18, v252, 10
	v_readlane_b32 s19, v252, 11
	v_readlane_b32 s20, v252, 12
	v_readlane_b32 s21, v252, 13
	v_readlane_b32 s24, v252, 16
	v_readlane_b32 s25, v252, 17
	v_readlane_b32 s26, v252, 18
	v_readlane_b32 s27, v252, 19
	s_branch .LBB0_110

.LBB0_110:
	s_add_i32 s4, s5, s92
	s_cmpk_gt_i32 s4, 0x5ff
	s_cselect_b64 s[0:1], -1, 0
	s_and_b64 vcc, exec, s[0:1]
	s_waitcnt vmcnt(1)
	ds_write2_b32 v16, v0, v1 offset1:1
	ds_write2_b32 v16, v2, v3 offset0:2 offset1:3
	s_waitcnt vmcnt(0)
	ds_write2_b32 v17, v4, v5 offset1:1
	ds_write2_b32 v17, v6, v7 offset0:2 offset1:3
	s_cbranch_vccnz .LBB0_109
	s_mul_hi_i32 s6, s4, 0x2aaaaaab
	s_lshr_b32 s7, s6, 31
	s_lshr_b32 s6, s6, 8
	s_add_i32 s6, s6, s7
	s_mulk_i32 s6, 0x600
	s_sub_i32 s6, s4, s6
	s_sext_i32_i16 s7, s6
	s_mulk_i32 s7, 0x2aab
	s_lshr_b32 s12, s7, 31
	s_ashr_i32 s7, s7, 20
	s_add_i32 s7, s7, s12
	s_mul_i32 s12, s7, 0x60
	s_sub_i32 s6, s6, s12
	s_sext_i32_i16 s6, s6
	s_lshl_b32 s6, s6, 6
	s_lshl_b32 s12, s7, 6
	s_ashr_i32 s7, s6, 31
	v_lshl_add_u64 v[0:1], s[6:7], 2, v[10:11]
	v_add_u32_e32 v2, s12, v12
	v_mad_i64_i32 v[20:21], s[6:7], v2, s3, v[0:1]
	v_add_u32_e32 v2, s12, v13
	v_mad_i64_i32 v[22:23], s[6:7], v2, s3, v[0:1]
	global_load_dwordx4 v[0:3], v[20:21], off nt
	global_load_dwordx4 v[4:7], v[22:23], off nt
	s_branch .LBB0_109
.LBB0_112:
	s_add_u32 s0, s42, 0xcc00000
	v_writelane_b32 v252, s0, 24
	s_addc_u32 s0, s43, 0
	v_writelane_b32 v252, s0, 25
	v_mov_b32_e32 v10, v170
	s_cmpk_gt_i32 s85, 0x7ff
	s_cbranch_scc1 .LBB0_117
	s_ashr_i32 s0, s85, 31
	s_lshr_b32 s0, s0, 22
	s_add_i32 s1, s85, s0
	s_ashr_i32 s0, s1, 10
	s_and_b32 s1, s1, 0xfc00
	s_sub_i32 s1, s85, s1
	s_sext_i32_i16 s3, s1
	s_bfe_u32 s3, s3, 0x60019
	s_add_i32 s3, s1, s3
	s_sext_i32_i16 s4, s3
	s_and_b32 s3, s3, 0xffc0
	s_sub_i32 s1, s1, s3
	s_sext_i32_i16 s3, s1
	s_ashr_i32 s1, s0, 31
	v_readlane_b32 s12, v252, 4
	s_lshl_b64 s[0:1], s[0:1], 24
	v_readlane_b32 s24, v252, 16
	v_readlane_b32 s25, v252, 17
	s_add_u32 s5, s24, s0
	s_addc_u32 s6, s25, s1
	s_lshl_b32 s0, s3, 6
	s_ashr_i32 s1, s0, 31
	s_andn2_b32 s4, s4, 63
	s_lshl_b64 s[0:1], s[0:1], 2
	s_waitcnt vmcnt(2)
	v_lshlrev_b32_e32 v0, 2, v10
	v_ashrrev_i32_e32 v12, 4, v10
	s_add_u32 s0, s5, s0
	v_and_b32_e32 v18, 60, v0
	v_add_u32_e32 v2, s4, v12
	s_addc_u32 s1, s6, s1
	v_mov_b32_e32 v9, 0
	v_lshlrev_b32_e32 v8, 2, v18
	v_ashrrev_i32_e32 v3, 31, v2
	v_lshl_add_u64 v[0:1], s[0:1], 0, v[8:9]
	v_lshlrev_b64 v[2:3], 14, v[2:3]
	v_lshl_add_u64 v[14:15], v[0:1], 0, v[2:3]
	v_add_u32_e32 v2, 0x200, v10
	v_ashrrev_i32_e32 v13, 4, v2
	v_add_u32_e32 v2, s4, v13
	v_ashrrev_i32_e32 v3, 31, v2
	v_lshlrev_b64 v[2:3], 14, v[2:3]
	v_lshl_add_u64 v[16:17], v[0:1], 0, v[2:3]
	global_load_dwordx4 v[0:3], v[14:15], off nt
	global_load_dwordx4 v[4:7], v[16:17], off nt
	v_add_u32_e32 v11, 0, v8
	v_lshlrev_b32_e32 v8, 3, v10
	v_ashrrev_i32_e32 v14, 3, v10
	v_and_b32_e32 v8, 56, v8
	s_movk_i32 s0, 0x104
	v_mul_u32_u24_e32 v10, 0x104, v8
	v_lshlrev_b32_e32 v15, 2, v14
	v_add3_u32 v15, 0, v10, v15
	v_mul_lo_u32 v10, v12, s0
	v_mul_lo_u32 v17, v13, s0
	v_add_u32_e32 v16, v11, v10
	v_add_u32_e32 v17, v11, v17
	v_lshlrev_b32_e32 v10, 2, v18
	v_lshlrev_b32_e32 v8, 1, v8
	s_mov_b32 s4, s85
	v_readlane_b32 s13, v252, 5
	v_readlane_b32 s14, v252, 6
	v_readlane_b32 s15, v252, 7
	v_readlane_b32 s16, v252, 8
	v_readlane_b32 s17, v252, 9
	v_readlane_b32 s18, v252, 10
	v_readlane_b32 s19, v252, 11
	v_readlane_b32 s20, v252, 12
	v_readlane_b32 s21, v252, 13
	v_readlane_b32 s22, v252, 14
	v_readlane_b32 s23, v252, 15
	v_readlane_b32 s26, v252, 18
	v_readlane_b32 s27, v252, 19
	s_branch .LBB0_115

.LBB0_115:
	s_add_i32 s3, s4, s92
	s_cmpk_gt_i32 s3, 0x7ff
	s_cselect_b64 s[0:1], -1, 0
	s_and_b64 vcc, exec, s[0:1]
	s_waitcnt vmcnt(1)
	ds_write2_b32 v16, v0, v1 offset1:1
	ds_write2_b32 v16, v2, v3 offset0:2 offset1:3
	s_waitcnt vmcnt(0)
	ds_write2_b32 v17, v4, v5 offset1:1
	ds_write2_b32 v17, v6, v7 offset0:2 offset1:3
	s_cbranch_vccnz .LBB0_114
	s_ashr_i32 s5, s3, 31
	s_lshr_b32 s5, s5, 22
	s_add_i32 s5, s3, s5
	s_ashr_i32 s6, s5, 10
	s_and_b32 s5, s5, 0xfc00
	s_sub_i32 s5, s3, s5
	s_sext_i32_i16 s7, s5
	s_bfe_u32 s7, s7, 0x60019
	s_add_i32 s7, s5, s7
	s_sext_i32_i16 s12, s7
	s_and_b32 s7, s7, 0xffc0
	s_sub_i32 s5, s5, s7
	s_ashr_i32 s7, s6, 31
	v_readlane_b32 s16, v252, 4
	s_lshl_b64 s[6:7], s[6:7], 24
	v_readlane_b32 s28, v252, 16
	s_sext_i32_i16 s5, s5
	v_readlane_b32 s29, v252, 17
	s_add_u32 s13, s28, s6
	s_addc_u32 s14, s29, s7
	s_lshl_b32 s6, s5, 6
	s_ashr_i32 s7, s6, 31
	s_andn2_b32 s12, s12, 63
	s_lshl_b64 s[6:7], s[6:7], 2
	s_add_u32 s6, s13, s6
	v_add_u32_e32 v2, s12, v12
	s_addc_u32 s7, s14, s7
	v_mov_b32_e32 v11, v9
	v_ashrrev_i32_e32 v3, 31, v2
	v_lshl_add_u64 v[0:1], s[6:7], 0, v[10:11]
	v_lshlrev_b64 v[2:3], 14, v[2:3]
	v_lshl_add_u64 v[18:19], v[0:1], 0, v[2:3]
	v_add_u32_e32 v2, s12, v13
	v_ashrrev_i32_e32 v3, 31, v2
	v_lshlrev_b64 v[2:3], 14, v[2:3]
	v_lshl_add_u64 v[20:21], v[0:1], 0, v[2:3]
	global_load_dwordx4 v[0:3], v[18:19], off nt
	global_load_dwordx4 v[4:7], v[20:21], off nt
	v_readlane_b32 s17, v252, 5
	v_readlane_b32 s18, v252, 6
	v_readlane_b32 s19, v252, 7
	v_readlane_b32 s20, v252, 8
	v_readlane_b32 s21, v252, 9
	v_readlane_b32 s22, v252, 10
	v_readlane_b32 s23, v252, 11
	v_readlane_b32 s24, v252, 12
	v_readlane_b32 s25, v252, 13
	v_readlane_b32 s26, v252, 14
	v_readlane_b32 s27, v252, 15
	v_readlane_b32 s30, v252, 18
	v_readlane_b32 s31, v252, 19
	s_branch .LBB0_114

.LBB0_121:
	v_add_u32_e32 v32, 0xffff8000, v40
	v_ashrrev_i32_e32 v33, 31, v32
	v_readlane_b32 s44, v252, 4
	v_lshlrev_b64 v[24:25], 5, v[32:33]
	v_readlane_b32 s45, v252, 5
	v_readlane_b32 s46, v252, 6
	v_readlane_b32 s47, v252, 7
	v_lshl_add_u64 v[34:35], s[44:45], 0, v[24:25]
	global_load_dwordx4 v[24:27], v[34:35], off offset:16 nt
	global_load_dwordx4 v[28:31], v[34:35], off nt
	v_add_u32_e32 v34, s16, v40
	v_cmp_gt_i32_e32 vcc, s3, v34
	v_ashrrev_i32_e32 v35, 31, v34
	v_readlane_b32 s48, v252, 8
	v_readlane_b32 s49, v252, 9
	v_readlane_b32 s50, v252, 10
	v_readlane_b32 s51, v252, 11
	v_readlane_b32 s52, v252, 12
	v_readlane_b32 s53, v252, 13
	v_readlane_b32 s54, v252, 14
	v_readlane_b32 s55, v252, 15
	v_readlane_b32 s56, v252, 16
	v_readlane_b32 s57, v252, 17
	v_readlane_b32 s58, v252, 18
	v_readlane_b32 s59, v252, 19
	s_and_saveexec_b64 s[0:1], vcc
	s_cbranch_execz .LBB0_123
	v_readlane_b32 s44, v252, 4
	v_lshlrev_b64 v[0:1], 5, v[34:35]
	v_readlane_b32 s45, v252, 5
	v_readlane_b32 s46, v252, 6
	v_readlane_b32 s47, v252, 7
	v_lshl_add_u64 v[0:1], s[44:45], 0, v[0:1]
	global_load_dwordx4 v[8:11], v[0:1], off offset:16 nt
	s_nop 0
	global_load_dwordx4 v[0:3], v[0:1], off nt
	v_readlane_b32 s48, v252, 8
	v_readlane_b32 s49, v252, 9
	v_readlane_b32 s50, v252, 10
	v_readlane_b32 s51, v252, 11
	v_readlane_b32 s52, v252, 12
	v_readlane_b32 s53, v252, 13
	v_readlane_b32 s54, v252, 14
	v_readlane_b32 s55, v252, 15
	v_readlane_b32 s56, v252, 16
	v_readlane_b32 s57, v252, 17
	v_readlane_b32 s58, v252, 18
	v_readlane_b32 s59, v252, 19
.LBB0_123:
	s_or_b64 exec, exec, s[0:1]
	v_add_u32_e32 v36, s14, v40
	v_cmp_gt_i32_e64 s[0:1], s3, v36
	v_ashrrev_i32_e32 v37, 31, v36
	s_and_saveexec_b64 s[4:5], s[0:1]
	s_cbranch_execz .LBB0_125
	v_readlane_b32 s44, v252, 4
	v_lshlrev_b64 v[4:5], 5, v[36:37]
	v_readlane_b32 s45, v252, 5
	v_readlane_b32 s46, v252, 6
	v_readlane_b32 s47, v252, 7
	v_lshl_add_u64 v[4:5], s[44:45], 0, v[4:5]
	global_load_dwordx4 v[16:19], v[4:5], off offset:16 nt
	s_nop 0
	global_load_dwordx4 v[4:7], v[4:5], off nt
	v_readlane_b32 s48, v252, 8
	v_readlane_b32 s49, v252, 9
	v_readlane_b32 s50, v252, 10
	v_readlane_b32 s51, v252, 11
	v_readlane_b32 s52, v252, 12
	v_readlane_b32 s53, v252, 13
	v_readlane_b32 s54, v252, 14
	v_readlane_b32 s55, v252, 15
	v_readlane_b32 s56, v252, 16
	v_readlane_b32 s57, v252, 17
	v_readlane_b32 s58, v252, 18
	v_readlane_b32 s59, v252, 19
.LBB0_125:
	s_or_b64 exec, exec, s[4:5]
	v_add_u32_e32 v38, s15, v40
	v_cmp_gt_i32_e64 s[4:5], s3, v38
	v_ashrrev_i32_e32 v39, 31, v38
	s_and_saveexec_b64 s[18:19], s[4:5]
	s_cbranch_execz .LBB0_127
	v_readlane_b32 s44, v252, 4
	v_lshlrev_b64 v[12:13], 5, v[38:39]
	v_readlane_b32 s45, v252, 5
	v_readlane_b32 s46, v252, 6
	v_readlane_b32 s47, v252, 7
	v_lshl_add_u64 v[12:13], s[44:45], 0, v[12:13]
	global_load_dwordx4 v[20:23], v[12:13], off offset:16 nt
	s_nop 0
	global_load_dwordx4 v[12:15], v[12:13], off nt
	v_readlane_b32 s48, v252, 8
	v_readlane_b32 s49, v252, 9
	v_readlane_b32 s50, v252, 10
	v_readlane_b32 s51, v252, 11
	v_readlane_b32 s52, v252, 12
	v_readlane_b32 s53, v252, 13
	v_readlane_b32 s54, v252, 14
	v_readlane_b32 s55, v252, 15
	v_readlane_b32 s56, v252, 16
	v_readlane_b32 s57, v252, 17
	v_readlane_b32 s58, v252, 18
	v_readlane_b32 s59, v252, 19
